# M2: decay scalars via s_load so their wait no longer drains the next item's 12 prefetch loads
# speedup vs baseline: 1.0165x; 1.0061x over previous
.LBB0_555:
	s_and_b32 s0, s4, 7
	s_lshl_b32 s1, s0, 2
	v_readlane_b32 s4, v255, 37
	v_mov_b32_e32 v60, s1
	v_readlane_b32 s5, v255, 38
	v_ashrrev_i32_e32 v155, 31, v154
	s_nop 3
	s_lshl_b32 s18, s0, 8
	s_load_dword s22, s[4:5], s1
	s_load_dword s0, s[4:5], s1 offset:0x20
	v_readlane_b32 s4, v252, 22
	v_ashrrev_i32_e32 v177, 4, v2
	v_lshlrev_b64 v[0:1], 11, v[154:155]
	v_readlane_b32 s5, v252, 23
	v_lshlrev_b32_e32 v172, 2, v177
	v_lshl_add_u64 v[0:1], s[4:5], 0, v[0:1]
	v_lshl_add_u64 v[0:1], v[0:1], 0, s[18:19]
	v_ashrrev_i32_e32 v173, 31, v172
	v_lshl_add_u64 v[0:1], v[172:173], 1, v[0:1]
	global_load_dwordx2 v[162:163], v[0:1], off
	global_load_dwordx2 v[160:161], v[0:1], off offset:32
	global_load_dwordx2 v[158:159], v[0:1], off offset:64
	global_load_dwordx2 v[156:157], v[0:1], off offset:96
	global_load_dwordx2 v[152:153], v[0:1], off offset:128
	global_load_dwordx2 v[150:151], v[0:1], off offset:160
	global_load_dwordx2 v[148:149], v[0:1], off offset:192
	s_nop 0
	global_load_dwordx2 v[0:1], v[0:1], off offset:224
	v_mul_u32_u24_e32 v62, 0xa0, v175
	v_and_b32_e32 v155, -16, v2
	v_add_u32_e32 v60, 1, v180
	v_sub_u32_e32 v61, 0x80, v180
	v_add3_u32 v136, 0, v62, v155
	v_cvt_f32_i32_e32 v124, v60
	v_cvt_f32_i32_e32 v125, v61
	s_waitcnt lgkmcnt(0)
	v_mov_b32_e32 v116, s22
	v_mov_b32_e32 v117, s0
	ds_read_b128 v[60:63], v136 offset:26624
	ds_read_b128 v[64:67], v136 offset:26688
	ds_read_b128 v[68:71], v136 offset:47104
	ds_read_b128 v[72:75], v136 offset:47168
	ds_read_b128 v[76:79], v136 offset:29184
	ds_read_b128 v[80:83], v136 offset:29248
	ds_read_b128 v[84:87], v136 offset:49664
	ds_read_b128 v[88:91], v136 offset:49728
	ds_read_b128 v[92:95], v136 offset:31744
	ds_read_b128 v[96:99], v136 offset:31808
	ds_read_b128 v[100:103], v136 offset:52224
	ds_read_b128 v[104:107], v136 offset:52288
	ds_read_b128 v[108:111], v136 offset:34304
	ds_read_b128 v[112:115], v136 offset:34368
	v_mul_f32_e32 v116, 0x3fb8aa3b, v116
	v_mul_f32_e32 v117, 0x3fb8aa3b, v117
	v_exp_f32_e32 v173, v116
	v_exp_f32_e32 v176, v117
	ds_read_b128 v[116:119], v136 offset:54784
	ds_read_b128 v[120:123], v136 offset:54848
	v_mul_f32_e64 v124, v124, -v173
	v_mul_f32_e64 v125, v125, -v176
	v_mul_f32_e32 v124, 0x3fb8aa3b, v124
	v_mul_f32_e32 v125, 0x3fb8aa3b, v125
	v_exp_f32_e32 v140, v124
	v_exp_f32_e32 v142, v125
	s_waitcnt lgkmcnt(14)
	v_mfma_f32_16x16x32_bf16 v[60:63], v[60:63], v[56:59], 0
	v_mfma_f32_16x16x32_bf16 v[60:63], v[64:67], v[52:55], v[60:63]
	s_waitcnt lgkmcnt(13)
	v_mfma_f32_16x16x32_bf16 v[64:67], v[68:71], v[56:59], 0
	s_waitcnt lgkmcnt(12)
	v_mfma_f32_16x16x32_bf16 v[64:67], v[72:75], v[52:55], v[64:67]
	s_waitcnt lgkmcnt(9)
	v_mfma_f32_16x16x32_bf16 v[72:75], v[84:87], v[56:59], 0
	v_mfma_f32_16x16x32_bf16 v[68:71], v[76:79], v[56:59], 0
	s_nop 4
	v_mul_f32_e64 v64, v142, v64
	v_mul_f32_e64 v65, v142, v65
	v_pk_mul_f32 v[66:67], v[142:143], v[66:67] op_sel_hi:[0,1]
	v_pk_fma_f32 v[60:61], v[140:141], v[60:61], v[64:65] op_sel_hi:[0,1,1]
	s_waitcnt lgkmcnt(8)
	v_mfma_f32_16x16x32_bf16 v[72:75], v[88:91], v[52:55], v[72:75]
	v_fma_f32 v62, v140, v62, v66
	v_fma_f32 v63, v140, v63, v67
	v_mfma_f32_16x16x32_bf16 v[68:71], v[80:83], v[52:55], v[68:71]
	s_waitcnt lgkmcnt(5)
	v_mfma_f32_16x16x32_bf16 v[80:83], v[100:103], v[56:59], 0
	s_nop 2
	v_mul_f32_e64 v64, v142, v74
	v_mul_f32_e64 v65, v142, v75
	v_pk_mul_f32 v[72:73], v[142:143], v[72:73] op_sel_hi:[0,1]
	v_pk_fma_f32 v[66:67], v[140:141], v[70:71], v[64:65] op_sel_hi:[0,1,1]
	v_mfma_f32_16x16x32_bf16 v[76:79], v[92:95], v[56:59], 0
	v_fma_f32 v64, v140, v68, v72
	v_fma_f32 v65, v140, v69, v73
	s_waitcnt lgkmcnt(1)
	v_mfma_f32_16x16x32_bf16 v[72:75], v[116:119], v[56:59], 0
	v_mfma_f32_16x16x32_bf16 v[80:83], v[104:107], v[52:55], v[80:83]
	v_mfma_f32_16x16x32_bf16 v[76:79], v[96:99], v[52:55], v[76:79]
	v_mfma_f32_16x16x32_bf16 v[84:87], v[108:111], v[56:59], 0
	s_nop 5
	v_mul_f32_e64 v68, v142, v82
	v_mul_f32_e64 v69, v142, v83
	v_pk_mul_f32 v[80:81], v[142:143], v[80:81] op_sel_hi:[0,1]
	v_pk_fma_f32 v[70:71], v[140:141], v[78:79], v[68:69] op_sel_hi:[0,1,1]
	s_waitcnt lgkmcnt(0)
	v_mfma_f32_16x16x32_bf16 v[72:75], v[120:123], v[52:55], v[72:75]
	v_fma_f32 v68, v140, v76, v80
	v_fma_f32 v69, v140, v77, v81
	s_nop 5
	v_pk_mul_f32 v[76:77], v[142:143], v[74:75] op_sel_hi:[0,1]
	v_pk_mul_f32 v[78:79], v[142:143], v[72:73] op_sel_hi:[0,1]
	v_mfma_f32_16x16x32_bf16 v[72:75], v[112:115], v[52:55], v[84:87]
	s_nop 7
	v_pk_fma_f32 v[74:75], v[140:141], v[74:75], v[76:77] op_sel_hi:[0,1,1]
	v_pk_fma_f32 v[72:73], v[140:141], v[72:73], v[78:79] op_sel_hi:[0,1,1]
	ds_read_b128 v[76:79], v136 offset:36864
	ds_read_b128 v[80:83], v136 offset:36928
	ds_read_b128 v[84:87], v136 offset:57344
	ds_read_b128 v[88:91], v136 offset:57408
	ds_read_b128 v[92:95], v136 offset:39424
	ds_read_b128 v[96:99], v136 offset:39488
	ds_read_b128 v[100:103], v136 offset:59904
	ds_read_b128 v[104:107], v136 offset:59968
	ds_read_b128 v[108:111], v136 offset:41984
	ds_read_b128 v[112:115], v136 offset:42048
	ds_read_b128 v[116:119], v136 offset:62464
	ds_read_b128 v[120:123], v136 offset:62528
	ds_read_b128 v[124:127], v136 offset:44544
	ds_read_b128 v[128:131], v136 offset:44608
	ds_read_b128 v[132:135], v136 offset:65024
	ds_read_b128 v[136:139], v136 offset:65088
	s_waitcnt lgkmcnt(14)
	v_mfma_f32_16x16x32_bf16 v[76:79], v[76:79], v[56:59], 0
	v_mfma_f32_16x16x32_bf16 v[76:79], v[80:83], v[52:55], v[76:79]
	s_waitcnt lgkmcnt(13)
	v_mfma_f32_16x16x32_bf16 v[80:83], v[84:87], v[56:59], 0
	s_waitcnt lgkmcnt(12)
	v_mfma_f32_16x16x32_bf16 v[80:83], v[88:91], v[52:55], v[80:83]
	s_waitcnt lgkmcnt(9)
	v_mfma_f32_16x16x32_bf16 v[88:91], v[100:103], v[56:59], 0
	v_mfma_f32_16x16x32_bf16 v[84:87], v[92:95], v[56:59], 0
	s_nop 4
	v_mul_f32_e64 v80, v142, v80
	v_mul_f32_e64 v81, v142, v81
	v_pk_mul_f32 v[82:83], v[142:143], v[82:83] op_sel_hi:[0,1]
	v_pk_fma_f32 v[76:77], v[140:141], v[76:77], v[80:81] op_sel_hi:[0,1,1]
	s_waitcnt lgkmcnt(8)
	v_mfma_f32_16x16x32_bf16 v[88:91], v[104:107], v[52:55], v[88:91]
	v_fma_f32 v78, v140, v78, v82
	v_fma_f32 v79, v140, v79, v83
	v_mfma_f32_16x16x32_bf16 v[84:87], v[96:99], v[52:55], v[84:87]
	s_waitcnt lgkmcnt(5)
	v_mfma_f32_16x16x32_bf16 v[96:99], v[116:119], v[56:59], 0
	s_nop 2
	v_mul_f32_e64 v80, v142, v90
	v_mul_f32_e64 v81, v142, v91
	v_pk_mul_f32 v[88:89], v[142:143], v[88:89] op_sel_hi:[0,1]
	v_pk_fma_f32 v[82:83], v[140:141], v[86:87], v[80:81] op_sel_hi:[0,1,1]
	v_mfma_f32_16x16x32_bf16 v[92:95], v[108:111], v[56:59], 0
	v_fma_f32 v80, v140, v84, v88
	v_fma_f32 v81, v140, v85, v89
	s_waitcnt lgkmcnt(1)
	v_mfma_f32_16x16x32_bf16 v[88:91], v[132:135], v[56:59], 0
	v_mfma_f32_16x16x32_bf16 v[96:99], v[120:123], v[52:55], v[96:99]
	v_mfma_f32_16x16x32_bf16 v[92:95], v[112:115], v[52:55], v[92:95]
	v_mfma_f32_16x16x32_bf16 v[100:103], v[124:127], v[56:59], 0
	s_nop 5
	v_mul_f32_e64 v84, v142, v98
	v_mul_f32_e64 v85, v142, v99
	v_pk_mul_f32 v[96:97], v[142:143], v[96:97] op_sel_hi:[0,1]
	v_pk_fma_f32 v[86:87], v[140:141], v[94:95], v[84:85] op_sel_hi:[0,1,1]
	s_waitcnt lgkmcnt(0)
	v_mfma_f32_16x16x32_bf16 v[88:91], v[136:139], v[52:55], v[88:91]
	v_fma_f32 v84, v140, v92, v96
	v_fma_f32 v85, v140, v93, v97
	s_nop 5
	v_pk_mul_f32 v[92:93], v[142:143], v[90:91] op_sel_hi:[0,1]
	v_pk_mul_f32 v[94:95], v[142:143], v[88:89] op_sel_hi:[0,1]
	v_mfma_f32_16x16x32_bf16 v[88:91], v[128:131], v[52:55], v[100:103]
	s_nop 7
	v_pk_fma_f32 v[90:91], v[140:141], v[90:91], v[92:93] op_sel_hi:[0,1,1]
	v_pk_fma_f32 v[88:89], v[140:141], v[88:89], v[94:95] op_sel_hi:[0,1,1]
	v_lshlrev_b32_e32 v93, 1, v2
	v_lshlrev_b32_e32 v92, 1, v175
	v_and_b32_e32 v93, 6, v93
	v_and_or_b32 v92, v92, 24, v93
	v_mul_u32_u24_e32 v92, 0xd0, v92
	v_add3_u32 v96, 0, v92, v155
	ds_read_b128 v[92:95], v96
	ds_read_b128 v[144:147], v96 offset:64
	ds_read_b128 v[182:185], v96 offset:208
	ds_read_b128 v[186:189], v96 offset:272
	ds_read_b128 v[140:143], v96 offset:6656
	ds_read_b128 v[136:139], v96 offset:6720
	ds_read_b128 v[132:135], v96 offset:6864
	ds_read_b128 v[112:115], v96 offset:6928
	ds_read_b128 v[128:131], v96 offset:13312
	ds_read_b128 v[124:127], v96 offset:13376
	ds_read_b128 v[120:123], v96 offset:13520
	ds_read_b128 v[116:119], v96 offset:13584
	ds_read_b128 v[108:111], v96 offset:19968
	ds_read_b128 v[104:107], v96 offset:20032
	ds_read_b128 v[100:103], v96 offset:20176
	ds_read_b128 v[96:99], v96 offset:20240
	v_lshlrev_b32_e32 v178, 3, v177
	v_sub_u32_e32 v179, v180, v178
	v_sub_u32_e32 v169, 0, v179
	v_max_i32_e32 v169, v179, v169
	v_cvt_f32_u32_e32 v169, v169
	v_cmp_gt_i32_e32 vcc, 0, v179
	v_add_u32_e32 v168, -1, v179
	s_waitcnt lgkmcnt(14)
	v_mfma_f32_16x16x32_bf16 v[92:95], v[92:95], v[56:59], 0
	v_cndmask_b32_e32 v181, v173, v176, vcc
	v_mul_f32_e64 v169, -v181, v169
	v_cmp_lt_i32_e32 vcc, 0, v179
	v_sub_u32_e32 v181, 1, v179
	v_mfma_f32_16x16x32_bf16 v[92:95], v[144:147], v[52:55], v[92:95]
	v_cndmask_b32_e32 v168, v181, v168, vcc
	v_cvt_f32_u32_e32 v168, v168
	v_cndmask_b32_e32 v181, v176, v173, vcc
	s_waitcnt lgkmcnt(13)
	v_mfma_f32_16x16x32_bf16 v[144:147], v[182:185], v[56:59], 0
	v_mul_f32_e32 v169, 0x3fb8aa3b, v169
	v_mul_f32_e64 v168, -v181, v168
	v_mul_f32_e32 v168, 0x3fb8aa3b, v168
	v_exp_f32_e32 v168, v168
	s_waitcnt lgkmcnt(12)
	v_mfma_f32_16x16x32_bf16 v[144:147], v[186:189], v[52:55], v[144:147]
	v_exp_f32_e32 v169, v169
	v_or_b32_e32 v181, 1, v178
	s_movk_i32 s22, 0x70
	v_cmp_gt_i32_e64 s[0:1], s22, v181
	v_cmp_gt_i32_e32 vcc, 14, v177
	s_and_b64 s[0:1], s[2:3], s[0:1]
	s_and_b64 s[4:5], s[2:3], vcc
	v_cndmask_b32_e64 v168, v168, 0, s[0:1]
	v_cndmask_b32_e64 v169, v169, 0, s[4:5]
	v_mul_f32_e32 v144, v168, v144
	v_or_b32_e32 v168, 2, v178
	v_mul_f32_e32 v92, v169, v92
	v_sub_u32_e32 v169, v180, v168
	v_sub_u32_e32 v182, 0, v169
	v_cmp_gt_i32_e32 vcc, 0, v169
	v_add_u32_e32 v181, -1, v169
	v_max_i32_e32 v182, v169, v182
	v_cndmask_b32_e32 v183, v173, v176, vcc
	v_cmp_lt_i32_e32 vcc, 0, v169
	v_sub_u32_e32 v169, 1, v169
	v_cvt_f32_u32_e32 v182, v182
	v_cndmask_b32_e32 v169, v169, v181, vcc
	v_cvt_f32_u32_e32 v169, v169
	v_cndmask_b32_e32 v181, v176, v173, vcc
	v_mul_f32_e64 v182, -v183, v182
	v_mul_f32_e32 v182, 0x3fb8aa3b, v182
	v_mul_f32_e64 v169, -v181, v169
	v_exp_f32_e32 v182, v182
	v_mul_f32_e32 v169, 0x3fb8aa3b, v169
	v_exp_f32_e32 v169, v169
	v_cmp_gt_i32_e32 vcc, s22, v168
	v_or_b32_e32 v168, 3, v178
	v_cmp_gt_i32_e64 s[0:1], s22, v168
	s_and_b64 s[4:5], s[2:3], vcc
	v_cndmask_b32_e64 v168, v182, 0, s[4:5]
	s_and_b64 s[0:1], s[2:3], s[0:1]
	v_cndmask_b32_e64 v169, v169, 0, s[0:1]
	v_mul_f32_e32 v93, v168, v93
	v_or_b32_e32 v168, 4, v178
	v_mul_f32_e32 v145, v169, v145
	v_sub_u32_e32 v169, v180, v168
	v_sub_u32_e32 v182, 0, v169
	v_cmp_gt_i32_e32 vcc, 0, v169
	v_add_u32_e32 v181, -1, v169
	v_max_i32_e32 v182, v169, v182
	v_cndmask_b32_e32 v183, v173, v176, vcc
	v_cmp_lt_i32_e32 vcc, 0, v169
	v_sub_u32_e32 v169, 1, v169
	v_cvt_f32_u32_e32 v182, v182
	v_cndmask_b32_e32 v169, v169, v181, vcc
	v_cvt_f32_u32_e32 v169, v169
	v_cndmask_b32_e32 v181, v176, v173, vcc
	v_mul_f32_e64 v182, -v183, v182
	v_mul_f32_e32 v182, 0x3fb8aa3b, v182
	v_mul_f32_e64 v169, -v181, v169
	v_exp_f32_e32 v182, v182
	v_mul_f32_e32 v169, 0x3fb8aa3b, v169
	v_exp_f32_e32 v169, v169
	v_cmp_gt_i32_e32 vcc, s22, v168
	v_or_b32_e32 v168, 5, v178
	v_cmp_gt_i32_e64 s[0:1], s22, v168
	s_and_b64 s[4:5], s[2:3], vcc
	v_cndmask_b32_e64 v168, v182, 0, s[4:5]
	s_and_b64 s[0:1], s[2:3], s[0:1]
	v_cndmask_b32_e64 v169, v169, 0, s[0:1]
	v_mul_f32_e32 v94, v168, v94
	v_or_b32_e32 v168, 6, v178
	s_waitcnt lgkmcnt(9)
	v_mfma_f32_16x16x32_bf16 v[132:135], v[132:135], v[56:59], 0
	v_mul_f32_e32 v146, v169, v146
	v_sub_u32_e32 v169, v180, v168
	v_sub_u32_e32 v181, 0, v169
	v_cmp_gt_i32_e32 vcc, 0, v169
	v_add_u32_e32 v180, -1, v169
	v_max_i32_e32 v181, v169, v181
	v_cndmask_b32_e32 v182, v173, v176, vcc
	v_cmp_lt_i32_e32 vcc, 0, v169
	v_sub_u32_e32 v169, 1, v169
	s_waitcnt lgkmcnt(8)
	v_mfma_f32_16x16x32_bf16 v[112:115], v[112:115], v[52:55], v[132:135]
	v_cndmask_b32_e32 v169, v169, v180, vcc
	v_cndmask_b32_e32 v180, v176, v173, vcc
	v_cmp_gt_i32_e32 vcc, s22, v168
	v_subrev_u32_e32 v132, 32, v179
	s_and_b64 s[4:5], s[2:3], vcc
	v_sub_u32_e32 v134, 32, v179
	v_cmp_gt_i32_e32 vcc, 0, v132
	v_cvt_f32_u32_e32 v169, v169
	v_subrev_u32_e32 v133, 33, v179
	v_max_i32_e32 v134, v132, v134
	v_cndmask_b32_e32 v135, v173, v176, vcc
	v_cmp_lt_i32_e32 vcc, 0, v132
	v_sub_u32_e32 v132, 33, v179
	v_cvt_f32_u32_e32 v181, v181
	v_cndmask_b32_e32 v132, v132, v133, vcc
	v_cvt_f32_u32_e32 v132, v132
	v_mul_f32_e64 v169, -v180, v169
	v_cvt_f32_u32_e32 v134, v134
	v_mul_f32_e32 v169, 0x3fb8aa3b, v169
	v_cndmask_b32_e32 v133, v176, v173, vcc
	v_exp_f32_e32 v169, v169
	v_mul_f32_e64 v132, -v133, v132
	v_mul_f32_e64 v181, -v182, v181
	v_or_b32_e32 v168, 7, v178
	v_mfma_f32_16x16x32_bf16 v[140:143], v[140:143], v[56:59], 0
	v_mul_f32_e32 v132, 0x3fb8aa3b, v132
	v_mul_f32_e32 v181, 0x3fb8aa3b, v181
	v_cmp_gt_i32_e64 s[0:1], s22, v168
	v_mul_f32_e64 v134, -v135, v134
	v_exp_f32_e32 v132, v132
	v_exp_f32_e32 v181, v181
	s_and_b64 s[0:1], s[2:3], s[0:1]
	v_mul_f32_e32 v134, 0x3fb8aa3b, v134
	v_add_u32_e32 v133, 33, v178
	v_cndmask_b32_e64 v169, v169, 0, s[0:1]
	v_exp_f32_e32 v134, v134
	v_cmp_gt_i32_e64 s[0:1], s22, v133
	v_mfma_f32_16x16x32_bf16 v[136:139], v[136:139], v[52:55], v[140:143]
	s_and_b64 s[0:1], s[2:3], s[0:1]
	v_cmp_gt_i32_e32 vcc, 10, v177
	v_cndmask_b32_e64 v132, v132, 0, s[0:1]
	v_cndmask_b32_e64 v168, v181, 0, s[4:5]
	s_and_b64 s[4:5], s[2:3], vcc
	v_mul_f32_e32 v112, v132, v112
	v_subrev_u32_e32 v132, 34, v179
	v_cndmask_b32_e64 v133, v134, 0, s[4:5]
	v_sub_u32_e32 v135, 34, v179
	v_cmp_gt_i32_e32 vcc, 0, v132
	v_mul_f32_e32 v133, v133, v136
	v_subrev_u32_e32 v134, 35, v179
	v_max_i32_e32 v135, v132, v135
	v_cndmask_b32_e32 v136, v173, v176, vcc
	v_cmp_lt_i32_e32 vcc, 0, v132
	v_sub_u32_e32 v132, 35, v179
	v_cvt_f32_u32_e32 v135, v135
	v_cndmask_b32_e32 v132, v132, v134, vcc
	v_cvt_f32_u32_e32 v132, v132
	v_cndmask_b32_e32 v134, v176, v173, vcc
	v_mul_f32_e64 v135, -v136, v135
	v_mul_f32_e32 v135, 0x3fb8aa3b, v135
	v_mul_f32_e64 v132, -v134, v132
	v_mul_f32_e32 v132, 0x3fb8aa3b, v132
	v_exp_f32_e32 v132, v132
	v_add_u32_e32 v134, 35, v178
	v_exp_f32_e32 v135, v135
	v_cmp_gt_i32_e32 vcc, s22, v134
	s_and_b64 s[0:1], s[2:3], vcc
	v_cndmask_b32_e64 v132, v132, 0, s[0:1]
	v_mul_f32_e32 v113, v132, v113
	v_subrev_u32_e32 v132, 36, v179
	v_cndmask_b32_e64 v134, v135, 0, s[4:5]
	v_sub_u32_e32 v136, 36, v179
	v_cmp_gt_i32_e32 vcc, 0, v132
	v_mul_f32_e32 v134, v134, v137
	v_subrev_u32_e32 v135, 37, v179
	v_max_i32_e32 v136, v132, v136
	v_cndmask_b32_e32 v137, v173, v176, vcc
	v_cmp_lt_i32_e32 vcc, 0, v132
	v_sub_u32_e32 v132, 37, v179
	v_cvt_f32_u32_e32 v136, v136
	v_cndmask_b32_e32 v132, v132, v135, vcc
	v_cvt_f32_u32_e32 v132, v132
	v_cndmask_b32_e32 v135, v176, v173, vcc
	v_mul_f32_e64 v136, -v137, v136
	v_mul_f32_e32 v136, 0x3fb8aa3b, v136
	v_mul_f32_e64 v132, -v135, v132
	v_mul_f32_e32 v132, 0x3fb8aa3b, v132
	v_exp_f32_e32 v132, v132
	v_add_u32_e32 v135, 37, v178
	v_exp_f32_e32 v136, v136
	v_cmp_gt_i32_e32 vcc, s22, v135
	s_and_b64 s[0:1], s[2:3], vcc
	v_cndmask_b32_e64 v132, v132, 0, s[0:1]
	v_mul_f32_e32 v114, v132, v114
	v_subrev_u32_e32 v132, 38, v179
	v_cndmask_b32_e64 v135, v136, 0, s[4:5]
	v_sub_u32_e32 v137, 38, v179
	v_cmp_gt_i32_e32 vcc, 0, v132
	v_mul_f32_e32 v135, v135, v138
	v_subrev_u32_e32 v136, 39, v179
	v_max_i32_e32 v137, v132, v137
	v_cndmask_b32_e32 v138, v173, v176, vcc
	v_cmp_lt_i32_e32 vcc, 0, v132
	v_sub_u32_e32 v132, 39, v179
	s_waitcnt lgkmcnt(5)
	v_mfma_f32_16x16x32_bf16 v[120:123], v[120:123], v[56:59], 0
	v_cndmask_b32_e32 v132, v132, v136, vcc
	v_cvt_f32_u32_e32 v132, v132
	v_cndmask_b32_e32 v136, v176, v173, vcc
	s_waitcnt lgkmcnt(4)
	v_mfma_f32_16x16x32_bf16 v[116:119], v[116:119], v[52:55], v[120:123]
	v_cvt_f32_u32_e32 v137, v137
	v_mul_f32_e64 v132, -v136, v132
	v_add_u32_e32 v136, 39, v178
	v_cmp_gt_i32_e32 vcc, s22, v136
	v_subrev_u32_e32 v120, 64, v179
	s_and_b64 s[0:1], s[2:3], vcc
	v_sub_u32_e32 v122, 64, v179
	v_cmp_gt_i32_e32 vcc, 0, v120
	v_add_u32_e32 v121, 0xffffffbf, v179
	v_max_i32_e32 v122, v120, v122
	v_cndmask_b32_e32 v123, v173, v176, vcc
	v_cmp_lt_i32_e32 vcc, 0, v120
	v_sub_u32_e32 v120, 0x41, v179
	v_cvt_f32_u32_e32 v122, v122
	v_cndmask_b32_e32 v120, v120, v121, vcc
	v_cvt_f32_u32_e32 v120, v120
	v_mul_f32_e32 v132, 0x3fb8aa3b, v132
	v_cndmask_b32_e32 v121, v176, v173, vcc
	v_exp_f32_e32 v132, v132
	v_mul_f32_e64 v120, -v121, v120
	v_mul_f32_e64 v137, -v138, v137
	v_mfma_f32_16x16x32_bf16 v[128:131], v[128:131], v[56:59], 0
	v_mul_f32_e32 v120, 0x3fb8aa3b, v120
	v_mul_f32_e32 v137, 0x3fb8aa3b, v137
	v_mul_f32_e64 v122, -v123, v122
	v_exp_f32_e32 v120, v120
	v_exp_f32_e32 v137, v137
	v_mul_f32_e32 v122, 0x3fb8aa3b, v122
	v_add_u32_e32 v121, 0x41, v178
	v_cndmask_b32_e64 v132, v132, 0, s[0:1]
	v_exp_f32_e32 v122, v122
	v_cmp_gt_i32_e64 s[0:1], s22, v121
	v_mfma_f32_16x16x32_bf16 v[124:127], v[124:127], v[52:55], v[128:131]
	s_and_b64 s[0:1], s[2:3], s[0:1]
	v_cmp_gt_i32_e32 vcc, 6, v177
	v_cndmask_b32_e64 v120, v120, 0, s[0:1]
	v_cndmask_b32_e64 v136, v137, 0, s[4:5]
	s_and_b64 s[4:5], s[2:3], vcc
	v_mul_f32_e32 v116, v120, v116
	v_add_u32_e32 v120, 0xffffffbe, v179
	v_cndmask_b32_e64 v121, v122, 0, s[4:5]
	v_sub_u32_e32 v123, 0x42, v179
	v_cmp_gt_i32_e32 vcc, 0, v120
	v_mul_f32_e32 v121, v121, v124
	v_add_u32_e32 v122, 0xffffffbd, v179
	v_max_i32_e32 v123, v120, v123
	v_cndmask_b32_e32 v124, v173, v176, vcc
	v_cmp_lt_i32_e32 vcc, 0, v120
	v_sub_u32_e32 v120, 0x43, v179
	v_cvt_f32_u32_e32 v123, v123
	v_cndmask_b32_e32 v120, v120, v122, vcc
	v_cvt_f32_u32_e32 v120, v120
	v_cndmask_b32_e32 v122, v176, v173, vcc
	v_mul_f32_e64 v123, -v124, v123
	v_mul_f32_e32 v123, 0x3fb8aa3b, v123
	v_mul_f32_e64 v120, -v122, v120
	v_mul_f32_e32 v120, 0x3fb8aa3b, v120
	v_exp_f32_e32 v120, v120
	v_add_u32_e32 v122, 0x43, v178
	v_exp_f32_e32 v123, v123
	v_cmp_gt_i32_e32 vcc, s22, v122
	s_and_b64 s[0:1], s[2:3], vcc
	v_cndmask_b32_e64 v120, v120, 0, s[0:1]
	v_mul_f32_e32 v117, v120, v117
	v_add_u32_e32 v120, 0xffffffbc, v179
	v_cndmask_b32_e64 v122, v123, 0, s[4:5]
	v_sub_u32_e32 v124, 0x44, v179
	v_cmp_gt_i32_e32 vcc, 0, v120
	v_mul_f32_e32 v122, v122, v125
	v_add_u32_e32 v123, 0xffffffbb, v179
	v_max_i32_e32 v124, v120, v124
	v_cndmask_b32_e32 v125, v173, v176, vcc
	v_cmp_lt_i32_e32 vcc, 0, v120
	v_sub_u32_e32 v120, 0x45, v179
	v_cvt_f32_u32_e32 v124, v124
	v_cndmask_b32_e32 v120, v120, v123, vcc
	v_cvt_f32_u32_e32 v120, v120
	v_cndmask_b32_e32 v123, v176, v173, vcc
	v_mul_f32_e64 v124, -v125, v124
	v_mul_f32_e32 v124, 0x3fb8aa3b, v124
	v_mul_f32_e64 v120, -v123, v120
	v_mul_f32_e32 v120, 0x3fb8aa3b, v120
	v_exp_f32_e32 v120, v120
	v_add_u32_e32 v123, 0x45, v178
	v_exp_f32_e32 v124, v124
	v_cmp_gt_i32_e32 vcc, s22, v123
	s_and_b64 s[0:1], s[2:3], vcc
	v_cndmask_b32_e64 v120, v120, 0, s[0:1]
	v_mul_f32_e32 v118, v120, v118
	v_add_u32_e32 v120, 0xffffffba, v179
	v_cndmask_b32_e64 v123, v124, 0, s[4:5]
	v_sub_u32_e32 v125, 0x46, v179
	v_cmp_gt_i32_e32 vcc, 0, v120
	v_mul_f32_e32 v123, v123, v126
	v_add_u32_e32 v124, 0xffffffb9, v179
	v_max_i32_e32 v125, v120, v125
	v_cndmask_b32_e32 v126, v173, v176, vcc
	v_cmp_lt_i32_e32 vcc, 0, v120
	v_sub_u32_e32 v120, 0x47, v179
	s_waitcnt lgkmcnt(3)
	v_mfma_f32_16x16x32_bf16 v[108:111], v[108:111], v[56:59], 0
	v_cndmask_b32_e32 v120, v120, v124, vcc
	v_cvt_f32_u32_e32 v120, v120
	v_cndmask_b32_e32 v124, v176, v173, vcc
	s_waitcnt lgkmcnt(1)
	v_mfma_f32_16x16x32_bf16 v[56:59], v[100:103], v[56:59], 0
	v_cvt_f32_u32_e32 v125, v125
	v_mul_f32_e64 v120, -v124, v120
	v_add_u32_e32 v124, 0x47, v178
	v_cmp_gt_i32_e32 vcc, s22, v124
	v_mfma_f32_16x16x32_bf16 v[104:107], v[104:107], v[52:55], v[108:111]
	s_and_b64 s[0:1], s[2:3], vcc
	v_mul_f32_e32 v120, 0x3fb8aa3b, v120
	v_exp_f32_e32 v120, v120
	s_waitcnt lgkmcnt(0)
	v_mfma_f32_16x16x32_bf16 v[52:55], v[96:99], v[52:55], v[56:59]
	v_mul_f32_e64 v125, -v126, v125
	v_mul_f32_e32 v125, 0x3fb8aa3b, v125
	v_exp_f32_e32 v125, v125
	v_add_u32_e32 v56, 0xffffffa0, v179
	v_sub_u32_e32 v58, 0x60, v179
	v_cmp_gt_i32_e32 vcc, 0, v56
	v_add_u32_e32 v57, 0xffffff9f, v179
	v_max_i32_e32 v58, v56, v58
	v_cndmask_b32_e32 v59, v173, v176, vcc
	v_cmp_lt_i32_e32 vcc, 0, v56
	v_sub_u32_e32 v56, 0x61, v179
	v_cvt_f32_u32_e32 v58, v58
	v_cndmask_b32_e32 v56, v56, v57, vcc
	v_cvt_f32_u32_e32 v56, v56
	v_cndmask_b32_e32 v57, v176, v173, vcc
	v_mul_f32_e64 v58, -v59, v58
	v_cndmask_b32_e64 v120, v120, 0, s[0:1]
	v_mul_f32_e64 v56, -v57, v56
	v_mul_f32_e32 v56, 0x3fb8aa3b, v56
	v_exp_f32_e32 v56, v56
	v_add_u32_e32 v57, 0x61, v178
	v_mul_f32_e32 v58, 0x3fb8aa3b, v58
	v_cmp_gt_i32_e64 s[0:1], s22, v57
	v_exp_f32_e32 v58, v58
	s_and_b64 s[0:1], s[2:3], s[0:1]
	v_cndmask_b32_e64 v56, v56, 0, s[0:1]
	v_cmp_gt_i32_e32 vcc, 2, v177
	v_mul_f32_e32 v52, v56, v52
	v_add_u32_e32 v56, 0xffffff9e, v179
	v_cndmask_b32_e64 v124, v125, 0, s[4:5]
	s_and_b64 s[4:5], s[2:3], vcc
	v_sub_u32_e32 v59, 0x62, v179
	v_cmp_gt_i32_e32 vcc, 0, v56
	v_cndmask_b32_e64 v57, v58, 0, s[4:5]
	v_add_u32_e32 v58, 0xffffff9d, v179
	v_max_i32_e32 v59, v56, v59
	v_cndmask_b32_e32 v96, v173, v176, vcc
	v_cmp_lt_i32_e32 vcc, 0, v56
	v_sub_u32_e32 v56, 0x63, v179
	v_cvt_f32_u32_e32 v59, v59
	v_cndmask_b32_e32 v56, v56, v58, vcc
	v_cvt_f32_u32_e32 v56, v56
	v_cndmask_b32_e32 v58, v176, v173, vcc
	v_mul_f32_e64 v59, -v96, v59
	v_mul_f32_e32 v59, 0x3fb8aa3b, v59
	v_mul_f32_e64 v56, -v58, v56
	v_mul_f32_e32 v56, 0x3fb8aa3b, v56
	v_exp_f32_e32 v56, v56
	v_add_u32_e32 v58, 0x63, v178
	v_cmp_gt_i32_e32 vcc, s22, v58
	v_exp_f32_e32 v59, v59
	s_and_b64 s[0:1], s[2:3], vcc
	v_cndmask_b32_e64 v56, v56, 0, s[0:1]
	v_mul_f32_e32 v53, v56, v53
	v_add_u32_e32 v56, 0xffffff9c, v179
	v_sub_u32_e32 v96, 0x64, v179
	v_cmp_gt_i32_e32 vcc, 0, v56
	v_cndmask_b32_e64 v58, v59, 0, s[4:5]
	v_add_u32_e32 v59, 0xffffff9b, v179
	v_max_i32_e32 v96, v56, v96
	v_cndmask_b32_e32 v97, v173, v176, vcc
	v_cmp_lt_i32_e32 vcc, 0, v56
	v_sub_u32_e32 v56, 0x65, v179
	v_cvt_f32_u32_e32 v96, v96
	v_cndmask_b32_e32 v56, v56, v59, vcc
	v_cvt_f32_u32_e32 v56, v56
	v_cndmask_b32_e32 v59, v176, v173, vcc
	v_mul_f32_e64 v96, -v97, v96
	v_mul_f32_e32 v96, 0x3fb8aa3b, v96
	v_mul_f32_e64 v56, -v59, v56
	v_mul_f32_e32 v56, 0x3fb8aa3b, v56
	v_exp_f32_e32 v56, v56
	v_add_u32_e32 v59, 0x65, v178
	v_cmp_gt_i32_e32 vcc, s22, v59
	v_exp_f32_e32 v96, v96
	s_and_b64 s[0:1], s[2:3], vcc
	v_cndmask_b32_e64 v56, v56, 0, s[0:1]
	v_mul_f32_e32 v54, v56, v54
	v_add_u32_e32 v56, 0xffffff9a, v179
	v_sub_u32_e32 v97, 0x66, v179
	v_cmp_gt_i32_e32 vcc, 0, v56
	v_cndmask_b32_e64 v59, v96, 0, s[4:5]
	v_add_u32_e32 v96, 0xffffff99, v179
	v_max_i32_e32 v97, v56, v97
	v_cndmask_b32_e32 v98, v173, v176, vcc
	v_cmp_lt_i32_e32 vcc, 0, v56
	v_sub_u32_e32 v56, 0x67, v179
	v_cvt_f32_u32_e32 v97, v97
	v_cndmask_b32_e32 v56, v56, v96, vcc
	v_cvt_f32_u32_e32 v56, v56
	v_cndmask_b32_e32 v96, v176, v173, vcc
	v_mul_f32_e64 v97, -v98, v97
	v_mul_f32_e32 v97, 0x3fb8aa3b, v97
	v_mul_f32_e64 v56, -v96, v56
	v_mul_f32_e32 v56, 0x3fb8aa3b, v56
	v_exp_f32_e32 v97, v97
	v_exp_f32_e32 v56, v56
	v_add_u32_e32 v96, 0x67, v178
	v_cmp_gt_i32_e32 vcc, s22, v96
	s_and_b64 s[0:1], s[2:3], vcc
	v_cndmask_b32_e64 v96, v97, 0, s[4:5]
	v_cndmask_b32_e64 v56, v56, 0, s[0:1]
	v_mul_f32_e32 v95, v168, v95
	v_mul_f32_e32 v147, v169, v147
	v_mul_f32_e32 v136, v136, v139
	v_mul_f32_e32 v115, v132, v115
	v_mul_f32_e32 v124, v124, v127
	v_mul_f32_e32 v119, v120, v119
	v_mul_f32_e32 v57, v57, v104
	v_mul_f32_e32 v58, v58, v105
	v_mul_f32_e32 v59, v59, v106
	v_mul_f32_e32 v96, v96, v107
	v_mul_f32_e32 v55, v56, v55
	v_mul_u32_u24_e32 v56, 0x120, v175
	v_readlane_b32 s0, v254, 59
	v_cvt_pk_bf16_f32 v92, v92, v144
	v_cvt_pk_bf16_f32 v93, v93, v145
	v_cvt_pk_bf16_f32 v94, v94, v146
	v_cvt_pk_bf16_f32 v95, v95, v147
	v_cvt_pk_bf16_f32 v112, v133, v112
	v_cvt_pk_bf16_f32 v113, v134, v113
	v_cvt_pk_bf16_f32 v114, v135, v114
	v_cvt_pk_bf16_f32 v115, v136, v115
	v_cvt_pk_bf16_f32 v116, v121, v116
	v_cvt_pk_bf16_f32 v117, v122, v117
	v_cvt_pk_bf16_f32 v118, v123, v118
	v_cvt_pk_bf16_f32 v119, v124, v119
	v_cvt_pk_bf16_f32 v52, v57, v52
	v_cvt_pk_bf16_f32 v53, v58, v53
	v_cvt_pk_bf16_f32 v54, v59, v54
	v_cvt_pk_bf16_f32 v55, v96, v55
	v_add3_u32 v155, s0, v56, v155
	ds_read_b128 v[56:59], v155
	ds_read_b128 v[96:99], v155 offset:64
	ds_read_b128 v[100:103], v155 offset:4608
	ds_read_b128 v[104:107], v155 offset:4672
	ds_read_b128 v[108:111], v155 offset:9216
	ds_read_b128 v[120:123], v155 offset:9280
	ds_read_b128 v[124:127], v155 offset:13824
	ds_read_b128 v[128:131], v155 offset:13888
	ds_read_b128 v[132:135], v155 offset:18432
	ds_read_b128 v[136:139], v155 offset:18496
	ds_read_b128 v[140:143], v155 offset:23040
	ds_read_b128 v[144:147], v155 offset:23104
	ds_read_b128 v[176:179], v155 offset:27648
	ds_read_b128 v[180:183], v155 offset:27712
	ds_read_b128 v[184:187], v155 offset:32256
	ds_read_b128 v[188:191], v155 offset:32320
	s_waitcnt lgkmcnt(14)
	v_mfma_f32_16x16x32_bf16 v[56:59], v[56:59], v[92:95], v[60:63]
	s_waitcnt lgkmcnt(13)
	v_mfma_f32_16x16x32_bf16 v[60:63], v[100:103], v[92:95], v[64:67]
	s_waitcnt lgkmcnt(11)
	v_mfma_f32_16x16x32_bf16 v[64:67], v[108:111], v[92:95], v[68:71]
	s_waitcnt lgkmcnt(9)
	v_mfma_f32_16x16x32_bf16 v[68:71], v[124:127], v[92:95], v[72:75]
	s_waitcnt lgkmcnt(7)
	v_mfma_f32_16x16x32_bf16 v[72:75], v[132:135], v[92:95], v[76:79]
	s_waitcnt lgkmcnt(5)
	v_mfma_f32_16x16x32_bf16 v[76:79], v[140:143], v[92:95], v[80:83]
	s_waitcnt lgkmcnt(3)
	v_mfma_f32_16x16x32_bf16 v[80:83], v[176:179], v[92:95], v[84:87]
	s_waitcnt lgkmcnt(1)
	v_mfma_f32_16x16x32_bf16 v[84:87], v[184:187], v[92:95], v[88:91]
	v_mfma_f32_16x16x32_bf16 v[56:59], v[96:99], v[112:115], v[56:59]
	v_mfma_f32_16x16x32_bf16 v[60:63], v[104:107], v[112:115], v[60:63]
	v_mfma_f32_16x16x32_bf16 v[64:67], v[120:123], v[112:115], v[64:67]
	v_mfma_f32_16x16x32_bf16 v[68:71], v[128:131], v[112:115], v[68:71]
	v_mfma_f32_16x16x32_bf16 v[72:75], v[136:139], v[112:115], v[72:75]
	v_mfma_f32_16x16x32_bf16 v[76:79], v[144:147], v[112:115], v[76:79]
	v_mfma_f32_16x16x32_bf16 v[80:83], v[180:183], v[112:115], v[80:83]
	s_waitcnt lgkmcnt(0)
	v_mfma_f32_16x16x32_bf16 v[84:87], v[188:191], v[112:115], v[84:87]
	ds_read_b128 v[88:91], v155 offset:128
	ds_read_b128 v[92:95], v155 offset:192
	ds_read_b128 v[96:99], v155 offset:4736
	ds_read_b128 v[100:103], v155 offset:4800
	ds_read_b128 v[104:107], v155 offset:9344
	ds_read_b128 v[108:111], v155 offset:9408
	ds_read_b128 v[112:115], v155 offset:13952
	ds_read_b128 v[120:123], v155 offset:14016
	ds_read_b128 v[124:127], v155 offset:18560
	ds_read_b128 v[128:131], v155 offset:18624
	ds_read_b128 v[132:135], v155 offset:23168
	ds_read_b128 v[136:139], v155 offset:23232
	ds_read_b128 v[140:143], v155 offset:27776
	ds_read_b128 v[144:147], v155 offset:27840
	ds_read_b128 v[176:179], v155 offset:32384
	ds_read_b128 v[180:183], v155 offset:32448
	s_waitcnt lgkmcnt(14)
	v_mfma_f32_16x16x32_bf16 v[56:59], v[88:91], v[116:119], v[56:59]
	s_waitcnt lgkmcnt(13)
	v_mfma_f32_16x16x32_bf16 v[60:63], v[96:99], v[116:119], v[60:63]
	s_waitcnt lgkmcnt(11)
	v_mfma_f32_16x16x32_bf16 v[64:67], v[104:107], v[116:119], v[64:67]
	s_waitcnt lgkmcnt(9)
	v_mfma_f32_16x16x32_bf16 v[68:71], v[112:115], v[116:119], v[68:71]
	s_waitcnt lgkmcnt(7)
	v_mfma_f32_16x16x32_bf16 v[88:91], v[124:127], v[116:119], v[72:75]
	s_waitcnt lgkmcnt(5)
	v_mfma_f32_16x16x32_bf16 v[96:99], v[132:135], v[116:119], v[76:79]
	s_waitcnt lgkmcnt(3)
	v_mfma_f32_16x16x32_bf16 v[104:107], v[140:143], v[116:119], v[80:83]
	s_waitcnt lgkmcnt(1)
	v_mfma_f32_16x16x32_bf16 v[84:87], v[176:179], v[116:119], v[84:87]
	v_mfma_f32_16x16x32_bf16 v[80:83], v[92:95], v[52:55], v[56:59]
	v_mfma_f32_16x16x32_bf16 v[76:79], v[100:103], v[52:55], v[60:63]
	v_mfma_f32_16x16x32_bf16 v[72:75], v[108:111], v[52:55], v[64:67]
	v_mfma_f32_16x16x32_bf16 v[68:71], v[120:123], v[52:55], v[68:71]
	v_mfma_f32_16x16x32_bf16 v[64:67], v[128:131], v[52:55], v[88:91]
	v_mfma_f32_16x16x32_bf16 v[60:63], v[136:139], v[52:55], v[96:99]
	v_mfma_f32_16x16x32_bf16 v[56:59], v[144:147], v[52:55], v[104:107]
	s_waitcnt lgkmcnt(0)
	v_mfma_f32_16x16x32_bf16 v[52:55], v[180:183], v[52:55], v[84:87]
	s_nop 2
	v_mov_b32_e32 v84, v80
	v_mov_b32_e32 v85, v76
	v_mov_b32_e32 v86, v81
	v_mov_b32_e32 v87, v77
	v_pk_add_f32 v[84:85], v[84:85], v[86:87]
	v_mov_b32_e32 v86, v82
	v_mov_b32_e32 v87, v78
	v_mov_b32_e32 v88, v83
	v_mov_b32_e32 v89, v79
	v_pk_add_f32 v[86:87], v[86:87], v[88:89]
	v_mov_b32_e32 v88, v72
	v_pk_add_f32 v[84:85], v[84:85], v[86:87]
	v_mov_b32_e32 v86, v73
	v_mov_b32_e32 v87, v74
	v_mov_b32_e32 v89, v75
	v_pk_add_f32 v[86:87], v[86:87], v[88:89]
	v_add_f32_e32 v84, 0, v84
	v_pk_add_f32 v[86:87], v[86:87], v[86:87] op_sel:[0,1] op_sel_hi:[1,0]
	v_add_f32_e32 v84, v84, v85
	v_add_f32_e32 v88, v68, v69
	v_add_f32_e32 v90, v70, v71
	v_mov_b32_e32 v85, v64
	v_mov_b32_e32 v87, v65
	v_mov_b32_e32 v89, v66
	v_mov_b32_e32 v91, v67
	v_pk_add_f32 v[84:85], v[84:85], v[86:87]
	v_pk_add_f32 v[86:87], v[88:89], v[90:91]
	v_mov_b32_e32 v88, v60
	v_pk_add_f32 v[84:85], v[84:85], v[86:87]
	v_mov_b32_e32 v86, v61
	v_mov_b32_e32 v87, v62
	v_mov_b32_e32 v89, v63
	v_pk_add_f32 v[86:87], v[86:87], v[88:89]
	v_pk_add_f32 v[84:85], v[84:85], v[84:85] op_sel:[0,1] op_sel_hi:[1,0]
	v_pk_add_f32 v[86:87], v[86:87], v[86:87] op_sel:[0,1] op_sel_hi:[1,0]
	v_add_f32_e32 v88, v56, v57
	v_add_f32_e32 v90, v58, v59
	v_mov_b32_e32 v85, v52
	v_mov_b32_e32 v87, v53
	v_mov_b32_e32 v89, v54
	v_mov_b32_e32 v91, v55
	v_pk_add_f32 v[84:85], v[84:85], v[86:87]
	v_pk_add_f32 v[86:87], v[88:89], v[90:91]
	v_and_b32_e32 v2, 16, v2
	v_pk_add_f32 v[84:85], v[84:85], v[86:87]
	v_and_b32_e32 v86, 64, v217
	v_add_f32_e32 v84, v84, v85
	v_xor_b32_e32 v85, 16, v217
	v_add_u32_e32 v86, 64, v86
	v_cmp_lt_i32_e32 vcc, v85, v86
	v_lshlrev_b32_e32 v2, 1, v2
	s_nop 0
	v_cndmask_b32_e32 v85, v217, v85, vcc
	v_lshlrev_b32_e32 v94, 2, v85
	ds_bpermute_b32 v85, v94, v84
	s_waitcnt lgkmcnt(0)
	v_add_f32_e32 v84, v84, v85
	v_xor_b32_e32 v85, 32, v217
	v_cmp_lt_i32_e32 vcc, v85, v86
	s_nop 1
	v_cndmask_b32_e32 v85, v217, v85, vcc
	v_lshlrev_b32_e32 v95, 2, v85
	ds_bpermute_b32 v85, v95, v84
	s_waitcnt lgkmcnt(0)
	v_add_f32_e32 v96, v84, v85
	v_fmamk_f32 v81, v96, 0xbc000000, v81
	v_fmamk_f32 v77, v96, 0xbc000000, v77
	v_fmamk_f32 v83, v96, 0xbc000000, v83
	v_fmac_f32_e32 v80, 0xbc000000, v96
	v_fmamk_f32 v79, v96, 0xbc000000, v79
	v_fmac_f32_e32 v76, 0xbc000000, v96
	v_mov_b32_e32 v86, v81
	v_mov_b32_e32 v87, v77
	v_fmamk_f32 v82, v96, 0xbc000000, v82
	v_fmamk_f32 v78, v96, 0xbc000000, v78
	v_mov_b32_e32 v84, v80
	v_mov_b32_e32 v85, v76
	v_pk_mul_f32 v[86:87], v[86:87], v[86:87]
	v_mov_b32_e32 v88, v83
	v_mov_b32_e32 v89, v79
	v_pk_fma_f32 v[84:85], v[84:85], v[84:85], v[86:87]
	v_mov_b32_e32 v86, v82
	v_mov_b32_e32 v87, v78
	v_pk_mul_f32 v[88:89], v[88:89], v[88:89]
	v_fmamk_f32 v73, v96, 0xbc000000, v73
	v_pk_fma_f32 v[86:87], v[86:87], v[86:87], v[88:89]
	v_fmamk_f32 v72, v96, 0xbc000000, v72
	v_pk_add_f32 v[84:85], v[84:85], v[86:87]
	v_fmamk_f32 v75, v96, 0xbc000000, v75
	v_fmac_f32_e32 v74, 0xbc000000, v96
	v_pk_add_f32 v[84:85], v[84:85], v[84:85] op_sel_hi:[0,1]
	v_pk_mul_f32 v[86:87], v[74:75], v[74:75]
	v_pk_mul_f32 v[88:89], v[72:73], v[72:73]
	v_fmamk_f32 v68, v96, 0xbc000000, v68
	v_pk_mov_b32 v[90:91], v[88:89], v[86:87] op_sel:[1,0]
	v_mov_b32_e32 v89, v87
	v_fmamk_f32 v69, v96, 0xbc000000, v69
	v_fmac_f32_e32 v70, 0xbc000000, v96
	v_mul_f32_e32 v84, v68, v68
	v_pk_add_f32 v[86:87], v[90:91], v[88:89]
	v_fmamk_f32 v71, v96, 0xbc000000, v71
	v_pk_fma_f32 v[88:89], v[68:69], v[68:69], v[84:85] op_sel_hi:[1,1,0]
	v_mul_f32_e32 v84, v70, v70
	v_pk_add_f32 v[86:87], v[86:87], v[86:87] op_sel_hi:[0,1]
	v_pk_fma_f32 v[90:91], v[70:71], v[70:71], v[84:85] op_sel_hi:[1,1,0]
	v_fmamk_f32 v67, v96, 0xbc000000, v67
	v_fmamk_f32 v66, v96, 0xbc000000, v66
	v_fmamk_f32 v65, v96, 0xbc000000, v65
	v_fmac_f32_e32 v64, 0xbc000000, v96
	v_mul_f32_e32 v88, v64, v64
	v_mul_f32_e32 v90, v65, v65
	v_mul_f32_e32 v86, v66, v66
	v_mul_f32_e32 v84, v67, v67
	v_pk_add_f32 v[88:89], v[88:89], v[90:91]
	v_pk_add_f32 v[84:85], v[86:87], v[84:85]
	v_fmamk_f32 v61, v96, 0xbc000000, v61
	v_fmamk_f32 v60, v96, 0xbc000000, v60
	v_fmamk_f32 v63, v96, 0xbc000000, v63
	v_fmac_f32_e32 v62, 0xbc000000, v96
	v_pk_add_f32 v[84:85], v[88:89], v[84:85]
	v_pk_mul_f32 v[86:87], v[62:63], v[62:63]
	v_pk_mul_f32 v[88:89], v[60:61], v[60:61]
	v_fmac_f32_e32 v58, 0xbc000000, v96
	v_pk_mov_b32 v[90:91], v[88:89], v[86:87] op_sel:[1,0]
	v_mov_b32_e32 v89, v87
	v_pk_add_f32 v[86:87], v[90:91], v[88:89]
	v_fmamk_f32 v88, v96, 0xbc000000, v56
	v_fmamk_f32 v89, v96, 0xbc000000, v57
	v_mul_f32_e32 v56, v88, v88
	v_pk_fma_f32 v[56:57], v[88:89], v[88:89], v[56:57] op_sel_hi:[1,1,0]
	v_fmamk_f32 v59, v96, 0xbc000000, v59
	v_mul_f32_e32 v56, v58, v58
	v_pk_add_f32 v[84:85], v[84:85], v[84:85] op_sel_hi:[0,1]
	v_pk_add_f32 v[86:87], v[86:87], v[86:87] op_sel_hi:[0,1]
	v_pk_fma_f32 v[90:91], v[58:59], v[58:59], v[56:57] op_sel_hi:[1,1,0]
	v_fmamk_f32 v93, v96, 0xbc000000, v55
	v_fmamk_f32 v92, v96, 0xbc000000, v54
	v_fmamk_f32 v53, v96, 0xbc000000, v53
	v_fmac_f32_e32 v52, 0xbc000000, v96
	v_mul_f32_e32 v56, v52, v52
	v_mul_f32_e32 v90, v53, v53
	v_mul_f32_e32 v86, v92, v92
	v_mul_f32_e32 v84, v93, v93
	v_pk_add_f32 v[54:55], v[56:57], v[90:91]
	v_pk_add_f32 v[56:57], v[86:87], v[84:85]
	v_mov_b64_e32 v[96:97], s[96:97]
	v_pk_add_f32 v[54:55], v[54:55], v[56:57]
	s_waitcnt vmcnt(7)
	v_lshlrev_b32_e32 v56, 16, v163
	v_add_f32_e32 v54, v54, v55
	ds_bpermute_b32 v55, v94, v54
	v_and_b32_e32 v57, 0xffff0000, v163
	s_waitcnt vmcnt(6)
	v_lshlrev_b32_e32 v90, 16, v160
	v_and_b32_e32 v91, 0xffff0000, v160
	v_lshlrev_b32_e32 v94, 16, v161
	s_waitcnt lgkmcnt(0)
	v_add_f32_e32 v54, v54, v55
	ds_bpermute_b32 v55, v95, v54
	v_and_b32_e32 v95, 0xffff0000, v161
	v_mad_i64_i32 v[96:97], s[0:1], v154, s48, v[96:97]
	v_and_b32_e32 v86, -8, v172
	s_waitcnt lgkmcnt(0)
	v_add_f32_e32 v54, v54, v55
	v_fmamk_f32 v54, v54, 0x3c000000, v219
	v_mul_f32_e32 v55, 0x4b800000, v54
	v_cmp_gt_f32_e32 vcc, s35, v54
	v_lshl_add_u64 v[96:97], v[96:97], 0, s[18:19]
	v_ashrrev_i32_e32 v87, 31, v86
	v_cndmask_b32_e32 v54, v54, v55, vcc
	v_rsq_f32_e32 v54, v54
	s_nop 0
	v_mul_f32_e32 v55, 0x45800000, v54
	v_cndmask_b32_e32 v84, v54, v55, vcc
	v_lshlrev_b32_e32 v54, 16, v162
	v_and_b32_e32 v55, 0xffff0000, v162
	v_pk_mul_f32 v[80:81], v[80:81], v[84:85] op_sel_hi:[1,0]
	v_pk_mul_f32 v[82:83], v[82:83], v[84:85] op_sel_hi:[1,0]
	v_pk_mul_f32 v[76:77], v[76:77], v[84:85] op_sel_hi:[1,0]
	v_pk_mul_f32 v[78:79], v[78:79], v[84:85] op_sel_hi:[1,0]
	v_pk_mul_f32 v[56:57], v[82:83], v[56:57]
	v_pk_mul_f32 v[54:55], v[80:81], v[54:55]
	v_pk_mul_f32 v[78:79], v[78:79], v[94:95]
	v_pk_mul_f32 v[76:77], v[76:77], v[90:91]
	v_cvt_pk_bf16_f32 v54, v54, v55
	v_cvt_pk_bf16_f32 v55, v56, v57
	v_cvt_pk_bf16_f32 v56, v76, v77
	v_cvt_pk_bf16_f32 v57, v78, v79
	v_lshl_add_u64 v[76:77], v[96:97], 0, v[2:3]
	v_permlane16_swap_b32_e32 v54, v56
	v_permlane16_swap_b32_e32 v55, v57
	v_lshl_add_u64 v[76:77], v[86:87], 1, v[76:77]
	global_store_dwordx4 v[76:77], v[54:57], off
	s_waitcnt vmcnt(5)
	v_lshlrev_b32_e32 v78, 16, v156
	v_and_b32_e32 v79, 0xffff0000, v156
	v_lshlrev_b32_e32 v54, 16, v158
	v_and_b32_e32 v55, 0xffff0000, v158
	v_lshlrev_b32_e32 v56, 16, v159
	v_and_b32_e32 v57, 0xffff0000, v159
	v_lshlrev_b32_e32 v80, 16, v157
	v_and_b32_e32 v81, 0xffff0000, v157
	v_pk_mul_f32 v[72:73], v[72:73], v[84:85] op_sel_hi:[1,0]
	v_pk_mul_f32 v[74:75], v[74:75], v[84:85] op_sel_hi:[1,0]
	v_pk_mul_f32 v[68:69], v[68:69], v[84:85] op_sel_hi:[1,0]
	v_pk_mul_f32 v[70:71], v[70:71], v[84:85] op_sel_hi:[1,0]
	v_pk_mul_f32 v[56:57], v[74:75], v[56:57]
	v_pk_mul_f32 v[54:55], v[72:73], v[54:55]
	v_pk_mul_f32 v[70:71], v[70:71], v[80:81]
	v_pk_mul_f32 v[68:69], v[68:69], v[78:79]
	v_cvt_pk_bf16_f32 v54, v54, v55
	v_cvt_pk_bf16_f32 v55, v56, v57
	v_cvt_pk_bf16_f32 v56, v68, v69
	v_cvt_pk_bf16_f32 v57, v70, v71
	s_nop 0
	v_permlane16_swap_b32_e32 v54, v56
	v_permlane16_swap_b32_e32 v55, v57
	global_store_dwordx4 v[76:77], v[54:57], off offset:64
	s_waitcnt vmcnt(4)
	v_lshlrev_b32_e32 v68, 16, v150
	v_and_b32_e32 v69, 0xffff0000, v150
	v_lshlrev_b32_e32 v54, 16, v152
	v_and_b32_e32 v55, 0xffff0000, v152
	v_lshlrev_b32_e32 v56, 16, v153
	v_and_b32_e32 v57, 0xffff0000, v153
	v_lshlrev_b32_e32 v70, 16, v151
	v_and_b32_e32 v71, 0xffff0000, v151
	v_pk_mul_f32 v[64:65], v[64:65], v[84:85] op_sel_hi:[1,0]
	v_pk_mul_f32 v[66:67], v[66:67], v[84:85] op_sel_hi:[1,0]
	v_pk_mul_f32 v[60:61], v[60:61], v[84:85] op_sel_hi:[1,0]
	v_pk_mul_f32 v[62:63], v[62:63], v[84:85] op_sel_hi:[1,0]
	v_pk_mul_f32 v[56:57], v[66:67], v[56:57]
	v_pk_mul_f32 v[54:55], v[64:65], v[54:55]
	v_pk_mul_f32 v[62:63], v[62:63], v[70:71]
	v_pk_mul_f32 v[60:61], v[60:61], v[68:69]
	v_cvt_pk_bf16_f32 v54, v54, v55
	v_cvt_pk_bf16_f32 v55, v56, v57
	v_cvt_pk_bf16_f32 v56, v60, v61
	v_cvt_pk_bf16_f32 v57, v62, v63
	s_nop 0
	v_permlane16_swap_b32_e32 v54, v56
	v_permlane16_swap_b32_e32 v55, v57
	global_store_dwordx4 v[76:77], v[54:57], off offset:128
	v_pk_mul_f32 v[58:59], v[58:59], v[84:85] op_sel_hi:[1,0]
	s_waitcnt vmcnt(3)
	v_lshlrev_b32_e32 v60, 16, v0
	v_lshlrev_b32_e32 v56, 16, v149
	v_and_b32_e32 v57, 0xffff0000, v149
	v_lshlrev_b32_e32 v54, 16, v148
	v_and_b32_e32 v55, 0xffff0000, v148
	v_and_b32_e32 v61, 0xffff0000, v0
	v_lshlrev_b32_e32 v0, 16, v1
	v_and_b32_e32 v1, 0xffff0000, v1
	v_pk_mul_f32 v[62:63], v[88:89], v[84:85] op_sel_hi:[1,0]
	v_pk_mul_f32 v[56:57], v[58:59], v[56:57]
	v_pk_mul_f32 v[52:53], v[52:53], v[84:85] op_sel_hi:[1,0]
	v_pk_mul_f32 v[58:59], v[92:93], v[84:85] op_sel_hi:[1,0]
	v_pk_mul_f32 v[54:55], v[62:63], v[54:55]
	v_pk_mul_f32 v[0:1], v[58:59], v[0:1]
	v_pk_mul_f32 v[58:59], v[52:53], v[60:61]
	v_cvt_pk_bf16_f32 v52, v54, v55
	v_cvt_pk_bf16_f32 v53, v56, v57
	v_cvt_pk_bf16_f32 v54, v58, v59
	v_cvt_pk_bf16_f32 v55, v0, v1
	s_nop 0
	v_permlane16_swap_b32_e32 v52, v54
	v_permlane16_swap_b32_e32 v53, v55
	global_store_dwordx4 v[76:77], v[52:55], off offset:192
	v_readlane_b32 s0, v254, 18
	s_waitcnt vmcnt(4)
	s_branch .Lret_join
